# stack2 + rows loop: dropped the top-of-loop vmcnt(0) so the next rows' loads issue while the previous rows' stores drain
# baseline (speedup 1.0000x reference)
; __device__ __forceinline__ void phase_rows(const Ctx& c, int l) {
;     ...
;         for (int q = 0; q < 2; ++q) { const int mr = min(m0 + q * NGW, MTOK - 1); const f32x4* xr = (const f32x4*)(src + (size_t)mr * DM) + lane;
; #pragma unroll
;             for (int j = 0; j < 4; ++j) v[q][j] = xr[64 * j]; }
; #pragma unroll
;         for (int q = 0; q < 2; ++q) {
;         const int m = m0 + q * NGW;
;         if (m >= MTOK) continue;
;         if (l > 0) {
;             float s = 0.f;
; #pragma unroll
;             for (int j = 0; j < 4; ++j) s += (v[q][j].x + v[q][j].y) + (v[q][j].z + v[q][j].w);
;             const float mean = wave_sum(s) * (1.f / DM); float s2 = 0.f;
; #pragma unroll
;             for (int j = 0; j < 4; ++j) { v[q][j] = v[q][j] - mean; s2 += (v[q][j].x * v[q][j].x + v[q][j].y * v[q][j].y) + (v[q][j].z * v[q][j].z + v[q][j].w * v[q][j].w); }
;             const float rstd = 1.f / sqrtf(wave_sum(s2) * (1.f / DM) + LN_EPS);
;             const f32x4* gp = (const f32x4*)(c.inp(IN_LNG) + (size_t)(l - 1) * DM) + lane; const f32x4* bp = (const f32x4*)(c.inp(IN_LNB) + (size_t)(l - 1) * DM) + lane;
;             f32x4* orow = (f32x4*)(c.out + (size_t)m * DM) + lane;
; #pragma unroll
;             for (int j = 0; j < 4; ++j) { v[q][j] = v[q][j] * rstd * gp[64 * j] + bp[64 * j]; if (l == NLAYER) orow[64 * j] = v[q][j]; }
.LBB0_487:
	s_add_i32 s54, s46, s26
	s_ashr_i32 s47, s46, 31
	s_min_i32 s16, s54, 0x7fff
	s_lshl_b64 s[60:61], s[46:47], 12
	s_ashr_i32 s17, s16, 31
	v_lshl_add_u64 v[138:139], v[174:175], 0, s[60:61]
	s_lshl_b64 s[16:17], s[16:17], 12
	global_load_dwordx4 v[166:169], v[138:139], off nt
	global_load_dwordx4 v[162:165], v[138:139], off offset:1024 nt
	global_load_dwordx4 v[158:161], v[138:139], off offset:2048 nt
	global_load_dwordx4 v[154:157], v[138:139], off offset:3072 nt
	v_lshl_add_u64 v[138:139], v[174:175], 0, s[16:17]
	global_load_dwordx4 v[150:153], v[138:139], off nt
	global_load_dwordx4 v[146:149], v[138:139], off offset:1024 nt
	global_load_dwordx4 v[142:145], v[138:139], off offset:2048 nt
	s_nop 0
	global_load_dwordx4 v[138:141], v[138:139], off offset:3072 nt
	v_cndmask_b32_e64 v96, 0, 1, s[48:49]
	v_cmp_ne_u32_e64 s[42:43], 1, v96
	s_andn2_b64 vcc, exec, s[48:49]
	s_cbranch_vccnz .LBB0_500
	s_waitcnt vmcnt(0)
	v_mov_b32_e32 v170, v167
	v_mov_b32_e32 v171, v168
	v_mov_b32_e32 v172, v166
	v_mov_b32_e32 v173, v169
	v_pk_add_f32 v[170:171], v[170:171], v[172:173]
	v_mov_b32_e32 v172, v163
	v_mov_b32_e32 v173, v164
	v_mov_b32_e32 v180, v162
	v_mov_b32_e32 v181, v165
	v_pk_add_f32 v[172:173], v[172:173], v[180:181]
	v_add_f32_e32 v96, v170, v171
	v_pk_add_f32 v[172:173], v[172:173], v[172:173] op_sel:[0,1] op_sel_hi:[1,0]
	v_add_f32_e32 v170, 0, v96
	v_add_f32_e32 v180, v158, v159
	v_add_f32_e32 v182, v160, v161
	v_mov_b32_e32 v171, v154
	v_mov_b32_e32 v173, v155
	v_mov_b32_e32 v181, v156
	v_mov_b32_e32 v183, v157
	v_pk_add_f32 v[170:171], v[170:171], v[172:173]
	v_pk_add_f32 v[172:173], v[180:181], v[182:183]
	s_load_dwordx4 s[64:67], s[12:13], 0x98
	v_pk_add_f32 v[170:171], v[170:171], v[172:173]
	v_lshl_add_u64 v[184:185], v[178:179], 0, s[60:61]
	v_add_f32_e32 v96, v170, v171
	s_nop 1
	v_add_f32_dpp v96, v96, v96 quad_perm:[1,0,3,2] row_mask:0xf bank_mask:0xf bound_ctrl:1
	s_nop 1
	v_add_f32_dpp v96, v96, v96 quad_perm:[2,3,0,1] row_mask:0xf bank_mask:0xf bound_ctrl:1
	s_nop 1
	v_add_f32_dpp v96, v96, v96 row_half_mirror row_mask:0xf bank_mask:0xf bound_ctrl:1
	s_nop 1
	v_add_f32_dpp v96, v96, v96 row_mirror row_mask:0xf bank_mask:0xf bound_ctrl:1
	s_nop 0
	v_readlane_b32 s0, v96, 16
	v_readlane_b32 s6, v96, 48
	v_readlane_b32 s16, v96, 0
	v_readlane_b32 s17, v96, 32
	v_mov_b32_e32 v170, s0
	v_mov_b32_e32 v171, s6
	v_pk_add_f32 v[170:171], s[16:17], v[170:171]
	s_nop 0
	v_add_f32_e32 v96, v170, v171
	v_fmamk_f32 v167, v96, 0xba800000, v167
	v_fmamk_f32 v166, v96, 0xba800000, v166
	v_fmamk_f32 v169, v96, 0xba800000, v169
	v_fmac_f32_e32 v168, 0xba800000, v96
	v_pk_mul_f32 v[170:171], v[168:169], v[168:169]
	v_pk_mul_f32 v[172:173], v[166:167], v[166:167]
	v_fmamk_f32 v183, v96, 0xba800000, v165
	v_pk_mov_b32 v[180:181], v[172:173], v[170:171] op_sel:[1,0]
	v_mov_b32_e32 v173, v171
	v_fmamk_f32 v182, v96, 0xba800000, v164
	v_fmamk_f32 v163, v96, 0xba800000, v163
	v_fmac_f32_e32 v162, 0xba800000, v96
	v_pk_add_f32 v[170:171], v[180:181], v[172:173]
	v_pk_mul_f32 v[164:165], v[182:183], v[182:183]
	v_pk_mul_f32 v[172:173], v[162:163], v[162:163]
	v_fmac_f32_e32 v158, 0xba800000, v96
	v_pk_mov_b32 v[180:181], v[172:173], v[164:165] op_sel:[1,0]
	v_mov_b32_e32 v173, v165
	v_pk_add_f32 v[164:165], v[180:181], v[172:173]
	v_fmamk_f32 v160, v96, 0xba800000, v160
	v_pk_add_f32 v[164:165], v[164:165], v[164:165] op_sel_hi:[0,1]
	v_fmamk_f32 v159, v96, 0xba800000, v159
	v_mul_f32_e32 v164, v158, v158
	v_fmamk_f32 v161, v96, 0xba800000, v161
	v_pk_fma_f32 v[172:173], v[158:159], v[158:159], v[164:165] op_sel_hi:[1,1,0]
	v_mul_f32_e32 v164, v160, v160
	v_pk_add_f32 v[170:171], v[170:171], v[170:171] op_sel_hi:[0,1]
	v_pk_fma_f32 v[180:181], v[160:161], v[160:161], v[164:165] op_sel_hi:[1,1,0]
	v_fmamk_f32 v157, v96, 0xba800000, v157
	v_fmamk_f32 v156, v96, 0xba800000, v156
	v_fmamk_f32 v155, v96, 0xba800000, v155
	v_fmac_f32_e32 v154, 0xba800000, v96
	v_mul_f32_e32 v172, v154, v154
	v_mul_f32_e32 v180, v155, v155
	v_mul_f32_e32 v170, v156, v156
	v_mul_f32_e32 v164, v157, v157
	v_pk_add_f32 v[172:173], v[172:173], v[180:181]
	v_pk_add_f32 v[164:165], v[170:171], v[164:165]
	s_nop 0
	v_pk_add_f32 v[164:165], v[172:173], v[164:165]
	s_nop 0
	v_add_f32_e32 v164, v164, v165
	s_nop 1
	v_add_f32_dpp v164, v164, v164 quad_perm:[1,0,3,2] row_mask:0xf bank_mask:0xf bound_ctrl:1
	s_nop 1
	v_add_f32_dpp v164, v164, v164 quad_perm:[2,3,0,1] row_mask:0xf bank_mask:0xf bound_ctrl:1
	s_nop 1
	v_add_f32_dpp v164, v164, v164 row_half_mirror row_mask:0xf bank_mask:0xf bound_ctrl:1
	s_nop 1
	v_add_f32_dpp v164, v164, v164 row_mirror row_mask:0xf bank_mask:0xf bound_ctrl:1
	s_nop 0
	v_readlane_b32 s0, v164, 16
	v_readlane_b32 s6, v164, 48
	v_readlane_b32 s16, v164, 0
	v_readlane_b32 s17, v164, 32
	v_mov_b32_e32 v164, s0
	v_mov_b32_e32 v165, s6
	v_pk_add_f32 v[164:165], s[16:17], v[164:165]
	s_nop 0
	v_add_f32_e32 v164, v164, v165
	v_fmamk_f32 v164, v164, 0x3a800000, v219
	v_cmp_gt_f32_e32 vcc, s87, v164
	v_mul_f32_e32 v165, 0x4f800000, v164
	s_nop 0
	v_cndmask_b32_e32 v164, v164, v165, vcc
	v_sqrt_f32_e32 v165, v164
	s_nop 0
	v_add_u32_e32 v170, -1, v165
	v_fma_f32 v171, -v170, v165, v164
	v_cmp_ge_f32_e64 s[40:41], 0, v171
	v_add_u32_e32 v171, 1, v165
	s_nop 0
	v_cndmask_b32_e64 v170, v165, v170, s[40:41]
	v_fma_f32 v165, -v171, v165, v164
	v_cmp_lt_f32_e64 s[40:41], 0, v165
	s_nop 1
	v_cndmask_b32_e64 v165, v170, v171, s[40:41]
	v_mul_f32_e32 v170, 0x37800000, v165
	v_cndmask_b32_e32 v165, v165, v170, vcc
	v_cmp_class_f32_e32 vcc, v164, v213
	s_nop 1
	v_cndmask_b32_e32 v164, v165, v164, vcc
	v_div_scale_f32 v165, s[16:17], v164, v164, 1.0
	v_rcp_f32_e32 v170, v165
	s_lshl_b64 s[16:17], s[22:23], 2
	s_waitcnt lgkmcnt(0)
	s_add_u32 s20, s64, s16
	s_addc_u32 s21, s65, s17
	v_fma_f32 v171, -v165, v170, 1.0
	v_fmac_f32_e32 v170, v171, v170
	v_div_scale_f32 v171, vcc, 1.0, v164, 1.0
	v_mul_f32_e32 v172, v171, v170
	v_fma_f32 v173, -v165, v172, v171
	v_fmac_f32_e32 v172, v173, v170
	v_fma_f32 v165, -v165, v172, v171
	v_div_fmas_f32 v165, v165, v170, v172
	v_div_fixup_f32 v180, v165, v164, 1.0
	v_lshlrev_b64 v[164:165], 4, v[200:201]
	s_add_u32 s16, s66, s16
	v_lshl_add_u64 v[186:187], s[20:21], 0, v[164:165]
	s_addc_u32 s17, s67, s17
	v_lshl_add_u64 v[188:189], s[16:17], 0, v[164:165]
	v_pk_mul_f32 v[190:191], v[166:167], v[180:181] op_sel_hi:[1,0]
	ds_read_b128 v[164:167], v251
	ds_read_b128 v[170:173], v251 offset:4096
	v_pk_mul_f32 v[168:169], v[168:169], v[180:181] op_sel_hi:[1,0]
	s_andn2_b64 vcc, exec, s[50:51]
	s_waitcnt lgkmcnt(0)
	v_pk_fma_f32 v[168:169], v[166:167], v[168:169], v[172:173]
	v_pk_fma_f32 v[166:167], v[164:165], v[190:191], v[170:171]
	v_cndmask_b32_e64 v164, 0, 1, s[50:51]
	v_cmp_ne_u32_e64 s[40:41], 1, v164
	s_cbranch_vccnz .LBB0_490
	global_store_dwordx4 v[184:185], v[166:169], off
